# attention: first K/Q fragments of the second sub-tile fetched under the first sub-tile's last PV MFMAs (defer8)
# baseline (speedup 1.0000x reference)
.Lnd_107:
	s_and_b32 s33, s42, 1
	s_mul_i32 s6, s33, 0x9000
	v_add_u32_e32 v199, s6, v187
	v_add_u32_e32 v198, s6, v188
	s_mov_b64 s[54:55], exec
	v_readfirstlane_b32 s4, v186
	s_bitcmp1_b32 s4, 8
	s_cbranch_scc1 .Lab_B
	ds_read_b128 v[216:219], v199 offset:0
	ds_read_b128 v[232:235], v193 offset:0
	ds_read_b128 v[220:223], v199 offset:32
	ds_read_b128 v[236:239], v193 offset:32
	ds_read_b128 v[224:227], v199 offset:64
	ds_read_b128 v[244:247], v193 offset:64
	ds_read_b128 v[228:231], v199 offset:96
	ds_read_b128 v[248:251], v193 offset:96
	s_waitcnt lgkmcnt(6)
	v_mfma_f32_32x32x16_bf16 v[144:159], v[216:219], v[232:235], v[0:15]
	s_waitcnt lgkmcnt(4)
	v_mfma_f32_32x32x16_bf16 v[144:159], v[220:223], v[236:239], v[144:159]
	s_waitcnt lgkmcnt(2)
	v_mfma_f32_32x32x16_bf16 v[144:159], v[224:227], v[244:247], v[144:159]
	s_waitcnt lgkmcnt(0)
	v_mfma_f32_32x32x16_bf16 v[144:159], v[228:231], v[248:251], v[144:159]
	ds_read_b128 v[216:219], v199 offset:9216
	ds_read_b128 v[232:235], v193 offset:36864
	ds_read_b128 v[220:223], v199 offset:9248
	ds_read_b128 v[236:239], v193 offset:36896
	ds_read_b128 v[224:227], v199 offset:9280
	ds_read_b128 v[244:247], v193 offset:36928
	ds_read_b128 v[228:231], v199 offset:9312
	ds_read_b128 v[248:251], v193 offset:36960
	s_nop 3
	v_exp_f32_e32 v144, v144
	v_exp_f32_e32 v145, v145
	v_exp_f32_e32 v146, v146
	v_exp_f32_e32 v147, v147
	v_exp_f32_e32 v148, v148
	v_exp_f32_e32 v149, v149
	v_exp_f32_e32 v150, v150
	v_exp_f32_e32 v151, v151
	v_exp_f32_e32 v152, v152
	v_exp_f32_e32 v153, v153
	v_exp_f32_e32 v154, v154
	v_exp_f32_e32 v155, v155
	v_exp_f32_e32 v156, v156
	v_exp_f32_e32 v157, v157
	v_exp_f32_e32 v158, v158
	v_exp_f32_e32 v159, v159
	v_add_f32_e32 v243, v144, v145
	v_add_f32_e32 v243, v146, v243
	v_add_f32_e32 v243, v147, v243
	v_add_f32_e32 v243, v148, v243
	v_add_f32_e32 v243, v149, v243
	v_add_f32_e32 v243, v150, v243
	v_add_f32_e32 v243, v151, v243
	s_waitcnt lgkmcnt(6)
	v_mfma_f32_32x32x16_bf16 v[200:215], v[216:219], v[232:235], v[0:15]
	s_waitcnt lgkmcnt(4)
	v_mfma_f32_32x32x16_bf16 v[200:215], v[220:223], v[236:239], v[200:215]
	s_waitcnt lgkmcnt(2)
	v_mfma_f32_32x32x16_bf16 v[200:215], v[224:227], v[244:247], v[200:215]
	s_waitcnt lgkmcnt(0)
	v_mfma_f32_32x32x16_bf16 v[200:215], v[228:231], v[248:251], v[200:215]
	ds_read_b128 v[216:219], v198 offset:0
	ds_read_b128 v[224:227], v198 offset:4608
	ds_read_b128 v[232:235], v198 offset:9216
	ds_read_b128 v[244:247], v198 offset:13824
	ds_read_b128 v[220:223], v198 offset:32
	ds_read_b128 v[228:231], v198 offset:4640
	ds_read_b128 v[236:239], v198 offset:9248
	ds_read_b128 v[248:251], v198 offset:13856
	v_add_f32_e32 v243, v152, v243
	v_add_f32_e32 v243, v153, v243
	v_add_f32_e32 v243, v154, v243
	v_add_f32_e32 v243, v155, v243
	v_add_f32_e32 v243, v156, v243
	v_add_f32_e32 v243, v157, v243
	v_add_f32_e32 v243, v158, v243
	v_add_f32_e32 v243, v159, v243
	v_add_f32_e32 v196, v196, v243
	v_cvt_pk_bf16_f32 v144, v144, v145
	v_cvt_pk_bf16_f32 v145, v146, v147
	v_cvt_pk_bf16_f32 v146, v148, v149
	v_cvt_pk_bf16_f32 v147, v150, v151
	v_cvt_pk_bf16_f32 v148, v152, v153
	v_cvt_pk_bf16_f32 v149, v154, v155
	v_cvt_pk_bf16_f32 v150, v156, v157
	v_cvt_pk_bf16_f32 v151, v158, v159
	s_waitcnt lgkmcnt(7)
	v_mfma_f32_32x32x16_bf16 v[112:127], v[216:219], v[144:147], v[112:127]
	v_exp_f32_e32 v200, v200
	v_exp_f32_e32 v201, v201
	v_exp_f32_e32 v202, v202
	v_exp_f32_e32 v203, v203
	v_exp_f32_e32 v204, v204
	s_waitcnt lgkmcnt(6)
	v_mfma_f32_32x32x16_bf16 v[80:95], v[224:227], v[144:147], v[80:95]
	v_exp_f32_e32 v205, v205
	v_exp_f32_e32 v206, v206
	v_exp_f32_e32 v207, v207
	v_exp_f32_e32 v208, v208
	v_exp_f32_e32 v209, v209
	s_waitcnt lgkmcnt(5)
	v_mfma_f32_32x32x16_bf16 v[48:63], v[232:235], v[144:147], v[48:63]
	v_exp_f32_e32 v210, v210
	v_exp_f32_e32 v211, v211
	v_exp_f32_e32 v212, v212
	v_exp_f32_e32 v213, v213
	v_exp_f32_e32 v214, v214
	s_waitcnt lgkmcnt(4)
	v_mfma_f32_32x32x16_bf16 v[16:31], v[244:247], v[144:147], v[16:31]
	v_exp_f32_e32 v215, v215
	v_add_f32_e32 v243, v200, v201
	v_add_f32_e32 v243, v202, v243
	v_add_f32_e32 v243, v203, v243
	v_add_f32_e32 v243, v204, v243
	s_waitcnt lgkmcnt(3)
	v_mfma_f32_32x32x16_bf16 v[112:127], v[220:223], v[148:151], v[112:127]
	v_add_f32_e32 v243, v205, v243
	v_add_f32_e32 v243, v206, v243
	v_add_f32_e32 v243, v207, v243
	v_add_f32_e32 v243, v208, v243
	v_add_f32_e32 v243, v209, v243
	s_waitcnt lgkmcnt(2)
	v_mfma_f32_32x32x16_bf16 v[80:95], v[228:231], v[148:151], v[80:95]
	v_add_f32_e32 v243, v210, v243
	v_add_f32_e32 v243, v211, v243
	v_add_f32_e32 v243, v212, v243
	v_add_f32_e32 v243, v213, v243
	v_add_f32_e32 v243, v214, v243
	s_waitcnt lgkmcnt(1)
	v_mfma_f32_32x32x16_bf16 v[48:63], v[236:239], v[148:151], v[48:63]
	v_add_f32_e32 v243, v215, v243
	v_add_f32_e32 v197, v197, v243
	v_cvt_pk_bf16_f32 v200, v200, v201
	v_cvt_pk_bf16_f32 v201, v202, v203
	v_cvt_pk_bf16_f32 v202, v204, v205
	s_waitcnt lgkmcnt(0)
	v_mfma_f32_32x32x16_bf16 v[16:31], v[248:251], v[148:151], v[16:31]
	v_cvt_pk_bf16_f32 v203, v206, v207
	v_cvt_pk_bf16_f32 v204, v208, v209
	v_cvt_pk_bf16_f32 v205, v210, v211
	v_cvt_pk_bf16_f32 v206, v212, v213
	v_cvt_pk_bf16_f32 v207, v214, v215
	ds_read_b128 v[252:255], v199 offset:4608
	ds_read_b128 v[208:211], v193
	ds_read_b128 v[212:215], v199 offset:4640
	v_mfma_f32_32x32x16_bf16 v[128:143], v[216:219], v[200:203], v[128:143]
	v_mfma_f32_32x32x16_bf16 v[96:111], v[224:227], v[200:203], v[96:111]
	v_mfma_f32_32x32x16_bf16 v[64:79], v[232:235], v[200:203], v[64:79]
	v_mfma_f32_32x32x16_bf16 v[32:47], v[244:247], v[200:203], v[32:47]
	v_mfma_f32_32x32x16_bf16 v[128:143], v[220:223], v[204:207], v[128:143]
	v_mfma_f32_32x32x16_bf16 v[96:111], v[228:231], v[204:207], v[96:111]
	v_mfma_f32_32x32x16_bf16 v[64:79], v[236:239], v[204:207], v[64:79]
	v_mfma_f32_32x32x16_bf16 v[32:47], v[248:251], v[204:207], v[32:47]
	ds_read_b128 v[236:239], v193 offset:32
	ds_read_b128 v[224:227], v199 offset:4672
	ds_read_b128 v[244:247], v193 offset:64
	ds_read_b128 v[228:231], v199 offset:4704
	ds_read_b128 v[248:251], v193 offset:96
	s_waitcnt lgkmcnt(6)
	v_mfma_f32_32x32x16_bf16 v[144:159], v[252:255], v[208:211], v[0:15]
	s_waitcnt lgkmcnt(4)
	v_mfma_f32_32x32x16_bf16 v[144:159], v[212:215], v[236:239], v[144:159]
	s_waitcnt lgkmcnt(2)
	v_mfma_f32_32x32x16_bf16 v[144:159], v[224:227], v[244:247], v[144:159]
	s_waitcnt lgkmcnt(0)
	v_mfma_f32_32x32x16_bf16 v[144:159], v[228:231], v[248:251], v[144:159]
	ds_read_b128 v[216:219], v199 offset:13824
	ds_read_b128 v[232:235], v193 offset:36864
	ds_read_b128 v[220:223], v199 offset:13856
	ds_read_b128 v[236:239], v193 offset:36896
	ds_read_b128 v[224:227], v199 offset:13888
	ds_read_b128 v[244:247], v193 offset:36928
	ds_read_b128 v[228:231], v199 offset:13920
	ds_read_b128 v[248:251], v193 offset:36960
	s_nop 3
	v_exp_f32_e32 v144, v144
	v_exp_f32_e32 v145, v145
	v_exp_f32_e32 v146, v146
	v_exp_f32_e32 v147, v147
	v_exp_f32_e32 v148, v148
	v_exp_f32_e32 v149, v149
	v_exp_f32_e32 v150, v150
	v_exp_f32_e32 v151, v151
	v_exp_f32_e32 v152, v152
	v_exp_f32_e32 v153, v153
	v_exp_f32_e32 v154, v154
	v_exp_f32_e32 v155, v155
	v_exp_f32_e32 v156, v156
	v_exp_f32_e32 v157, v157
	v_exp_f32_e32 v158, v158
	v_exp_f32_e32 v159, v159
	v_add_f32_e32 v243, v144, v145
	v_add_f32_e32 v243, v146, v243
	v_add_f32_e32 v243, v147, v243
	v_add_f32_e32 v243, v148, v243
	v_add_f32_e32 v243, v149, v243
	v_add_f32_e32 v243, v150, v243
	v_add_f32_e32 v243, v151, v243
	s_waitcnt lgkmcnt(6)
	v_mfma_f32_32x32x16_bf16 v[200:215], v[216:219], v[232:235], v[0:15]
	s_waitcnt lgkmcnt(4)
	v_mfma_f32_32x32x16_bf16 v[200:215], v[220:223], v[236:239], v[200:215]
	s_waitcnt lgkmcnt(2)
	v_mfma_f32_32x32x16_bf16 v[200:215], v[224:227], v[244:247], v[200:215]
	s_waitcnt lgkmcnt(0)
	v_mfma_f32_32x32x16_bf16 v[200:215], v[228:231], v[248:251], v[200:215]
	ds_read_b128 v[216:219], v198 offset:64
	ds_read_b128 v[224:227], v198 offset:4672
	ds_read_b128 v[232:235], v198 offset:9280
	ds_read_b128 v[244:247], v198 offset:13888
	ds_read_b128 v[220:223], v198 offset:96
	ds_read_b128 v[228:231], v198 offset:4704
	ds_read_b128 v[236:239], v198 offset:9312
	ds_read_b128 v[248:251], v198 offset:13920
	v_add_f32_e32 v243, v152, v243
	v_add_f32_e32 v243, v153, v243
	v_add_f32_e32 v243, v154, v243
	v_add_f32_e32 v243, v155, v243
	v_add_f32_e32 v243, v156, v243
	v_add_f32_e32 v243, v157, v243
	v_add_f32_e32 v243, v158, v243
	v_add_f32_e32 v243, v159, v243
	v_add_f32_e32 v196, v196, v243
	v_cvt_pk_bf16_f32 v144, v144, v145
	v_cvt_pk_bf16_f32 v145, v146, v147
	v_cvt_pk_bf16_f32 v146, v148, v149
	v_cvt_pk_bf16_f32 v147, v150, v151
	v_cvt_pk_bf16_f32 v148, v152, v153
	v_cvt_pk_bf16_f32 v149, v154, v155
	v_cvt_pk_bf16_f32 v150, v156, v157
	v_cvt_pk_bf16_f32 v151, v158, v159
	s_waitcnt lgkmcnt(7)
	v_mfma_f32_32x32x16_bf16 v[112:127], v[216:219], v[144:147], v[112:127]
	v_exp_f32_e32 v200, v200
	v_exp_f32_e32 v201, v201
	v_exp_f32_e32 v202, v202
	v_exp_f32_e32 v203, v203
	v_exp_f32_e32 v204, v204
	s_waitcnt lgkmcnt(6)
	v_mfma_f32_32x32x16_bf16 v[80:95], v[224:227], v[144:147], v[80:95]
	v_exp_f32_e32 v205, v205
	v_exp_f32_e32 v206, v206
	v_exp_f32_e32 v207, v207
	v_exp_f32_e32 v208, v208
	v_exp_f32_e32 v209, v209
	s_waitcnt lgkmcnt(5)
	v_mfma_f32_32x32x16_bf16 v[48:63], v[232:235], v[144:147], v[48:63]
	v_exp_f32_e32 v210, v210
	v_exp_f32_e32 v211, v211
	v_exp_f32_e32 v212, v212
	v_exp_f32_e32 v213, v213
	v_exp_f32_e32 v214, v214
	s_waitcnt lgkmcnt(4)
	v_mfma_f32_32x32x16_bf16 v[16:31], v[244:247], v[144:147], v[16:31]
	v_exp_f32_e32 v215, v215
	v_add_f32_e32 v243, v200, v201
	v_add_f32_e32 v243, v202, v243
	v_add_f32_e32 v243, v203, v243
	v_add_f32_e32 v243, v204, v243
	s_waitcnt lgkmcnt(3)
	v_mfma_f32_32x32x16_bf16 v[112:127], v[220:223], v[148:151], v[112:127]
	v_add_f32_e32 v243, v205, v243
	v_add_f32_e32 v243, v206, v243
	v_add_f32_e32 v243, v207, v243
	v_add_f32_e32 v243, v208, v243
	v_add_f32_e32 v243, v209, v243
	s_waitcnt lgkmcnt(2)
	v_mfma_f32_32x32x16_bf16 v[80:95], v[228:231], v[148:151], v[80:95]
	v_add_f32_e32 v243, v210, v243
	v_add_f32_e32 v243, v211, v243
	v_add_f32_e32 v243, v212, v243
	v_add_f32_e32 v243, v213, v243
	v_add_f32_e32 v243, v214, v243
	s_waitcnt lgkmcnt(1)
	v_mfma_f32_32x32x16_bf16 v[48:63], v[236:239], v[148:151], v[48:63]
	v_add_f32_e32 v243, v215, v243
	v_add_f32_e32 v197, v197, v243
	v_cvt_pk_bf16_f32 v200, v200, v201
	v_cvt_pk_bf16_f32 v201, v202, v203
	v_cvt_pk_bf16_f32 v202, v204, v205
	s_waitcnt lgkmcnt(0)
	v_mfma_f32_32x32x16_bf16 v[16:31], v[248:251], v[148:151], v[16:31]
	v_cvt_pk_bf16_f32 v203, v206, v207
	v_cvt_pk_bf16_f32 v204, v208, v209
	v_cvt_pk_bf16_f32 v205, v210, v211
	v_cvt_pk_bf16_f32 v206, v212, v213
	v_cvt_pk_bf16_f32 v207, v214, v215
	s_nop 1
	v_mfma_f32_32x32x16_bf16 v[128:143], v[216:219], v[200:203], v[128:143]
	v_mfma_f32_32x32x16_bf16 v[96:111], v[224:227], v[200:203], v[96:111]
	v_mfma_f32_32x32x16_bf16 v[64:79], v[232:235], v[200:203], v[64:79]
	v_mfma_f32_32x32x16_bf16 v[32:47], v[244:247], v[200:203], v[32:47]
	v_mfma_f32_32x32x16_bf16 v[128:143], v[220:223], v[204:207], v[128:143]
	v_mfma_f32_32x32x16_bf16 v[96:111], v[228:231], v[204:207], v[96:111]
	v_mfma_f32_32x32x16_bf16 v[64:79], v[236:239], v[204:207], v[64:79]
	v_mfma_f32_32x32x16_bf16 v[32:47], v[248:251], v[204:207], v[32:47]
	s_branch .LBB0_111

.Lab_B0:
	ds_read_b128 v[216:219], v199 offset:0
	ds_read_b128 v[232:235], v193 offset:0
	ds_read_b128 v[220:223], v199 offset:32
	ds_read_b128 v[236:239], v193 offset:32
	ds_read_b128 v[224:227], v199 offset:64
	ds_read_b128 v[244:247], v193 offset:64
	ds_read_b128 v[228:231], v199 offset:96
	ds_read_b128 v[248:251], v193 offset:96
	s_waitcnt lgkmcnt(6)
	v_mfma_f32_32x32x16_bf16 v[144:159], v[216:219], v[232:235], v[0:15]
	s_waitcnt lgkmcnt(4)
	v_mfma_f32_32x32x16_bf16 v[144:159], v[220:223], v[236:239], v[144:159]
	s_waitcnt lgkmcnt(2)
	v_mfma_f32_32x32x16_bf16 v[144:159], v[224:227], v[244:247], v[144:159]
	s_waitcnt lgkmcnt(0)
	v_mfma_f32_32x32x16_bf16 v[144:159], v[228:231], v[248:251], v[144:159]
	ds_read_b128 v[216:219], v199 offset:9216
	ds_read_b128 v[232:235], v193 offset:36864
	ds_read_b128 v[220:223], v199 offset:9248
	ds_read_b128 v[236:239], v193 offset:36896
	ds_read_b128 v[224:227], v199 offset:9280
	ds_read_b128 v[244:247], v193 offset:36928
	ds_read_b128 v[228:231], v199 offset:9312
	ds_read_b128 v[248:251], v193 offset:36960
	s_nop 3
	v_exp_f32_e32 v144, v144
	v_exp_f32_e32 v145, v145
	v_exp_f32_e32 v146, v146
	v_exp_f32_e32 v147, v147
	v_exp_f32_e32 v148, v148
	v_exp_f32_e32 v149, v149
	v_exp_f32_e32 v150, v150
	v_exp_f32_e32 v151, v151
	v_exp_f32_e32 v152, v152
	v_exp_f32_e32 v153, v153
	v_exp_f32_e32 v154, v154
	v_exp_f32_e32 v155, v155
	v_exp_f32_e32 v156, v156
	v_exp_f32_e32 v157, v157
	v_exp_f32_e32 v158, v158
	v_exp_f32_e32 v159, v159
	v_add_f32_e32 v243, v144, v145
	v_add_f32_e32 v243, v146, v243
	v_add_f32_e32 v243, v147, v243
	v_add_f32_e32 v243, v148, v243
	v_add_f32_e32 v243, v149, v243
	v_add_f32_e32 v243, v150, v243
	v_add_f32_e32 v243, v151, v243
	s_waitcnt lgkmcnt(6)
	v_mfma_f32_32x32x16_bf16 v[200:215], v[216:219], v[232:235], v[0:15]
	s_waitcnt lgkmcnt(4)
	v_mfma_f32_32x32x16_bf16 v[200:215], v[220:223], v[236:239], v[200:215]
	s_waitcnt lgkmcnt(2)
	v_mfma_f32_32x32x16_bf16 v[200:215], v[224:227], v[244:247], v[200:215]
	s_waitcnt lgkmcnt(0)
	v_mfma_f32_32x32x16_bf16 v[200:215], v[228:231], v[248:251], v[200:215]
	ds_read_b128 v[216:219], v198 offset:0
	ds_read_b128 v[224:227], v198 offset:4608
	ds_read_b128 v[232:235], v198 offset:9216
	ds_read_b128 v[244:247], v198 offset:13824
	ds_read_b128 v[220:223], v198 offset:32
	ds_read_b128 v[228:231], v198 offset:4640
	ds_read_b128 v[236:239], v198 offset:9248
	ds_read_b128 v[248:251], v198 offset:13856
	v_add_f32_e32 v243, v152, v243
	v_add_f32_e32 v243, v153, v243
	v_add_f32_e32 v243, v154, v243
	v_add_f32_e32 v243, v155, v243
	v_add_f32_e32 v243, v156, v243
	v_add_f32_e32 v243, v157, v243
	v_add_f32_e32 v243, v158, v243
	v_add_f32_e32 v243, v159, v243
	v_add_f32_e32 v196, v196, v243
	v_cvt_pk_bf16_f32 v144, v144, v145
	v_cvt_pk_bf16_f32 v145, v146, v147
	v_cvt_pk_bf16_f32 v146, v148, v149
	v_cvt_pk_bf16_f32 v147, v150, v151
	v_cvt_pk_bf16_f32 v148, v152, v153
	v_cvt_pk_bf16_f32 v149, v154, v155
	v_cvt_pk_bf16_f32 v150, v156, v157
	v_cvt_pk_bf16_f32 v151, v158, v159
	s_waitcnt lgkmcnt(7)
	v_mfma_f32_32x32x16_bf16 v[112:127], v[216:219], v[144:147], v[112:127]
	v_exp_f32_e32 v200, v200
	v_exp_f32_e32 v201, v201
	v_exp_f32_e32 v202, v202
	v_exp_f32_e32 v203, v203
	v_exp_f32_e32 v204, v204
	s_waitcnt lgkmcnt(6)
	v_mfma_f32_32x32x16_bf16 v[80:95], v[224:227], v[144:147], v[80:95]
	v_exp_f32_e32 v205, v205
	v_exp_f32_e32 v206, v206
	v_exp_f32_e32 v207, v207
	v_exp_f32_e32 v208, v208
	v_exp_f32_e32 v209, v209
	s_waitcnt lgkmcnt(5)
	v_mfma_f32_32x32x16_bf16 v[48:63], v[232:235], v[144:147], v[48:63]
	v_exp_f32_e32 v210, v210
	v_exp_f32_e32 v211, v211
	v_exp_f32_e32 v212, v212
	v_exp_f32_e32 v213, v213
	v_exp_f32_e32 v214, v214
	s_waitcnt lgkmcnt(4)
	v_mfma_f32_32x32x16_bf16 v[16:31], v[244:247], v[144:147], v[16:31]
	v_exp_f32_e32 v215, v215
	v_add_f32_e32 v243, v200, v201
	v_add_f32_e32 v243, v202, v243
	v_add_f32_e32 v243, v203, v243
	v_add_f32_e32 v243, v204, v243
	s_waitcnt lgkmcnt(3)
	v_mfma_f32_32x32x16_bf16 v[112:127], v[220:223], v[148:151], v[112:127]
	v_add_f32_e32 v243, v205, v243
	v_add_f32_e32 v243, v206, v243
	v_add_f32_e32 v243, v207, v243
	v_add_f32_e32 v243, v208, v243
	v_add_f32_e32 v243, v209, v243
	s_waitcnt lgkmcnt(2)
	v_mfma_f32_32x32x16_bf16 v[80:95], v[228:231], v[148:151], v[80:95]
	v_add_f32_e32 v243, v210, v243
	v_add_f32_e32 v243, v211, v243
	v_add_f32_e32 v243, v212, v243
	v_add_f32_e32 v243, v213, v243
	v_add_f32_e32 v243, v214, v243
	s_waitcnt lgkmcnt(1)
	v_mfma_f32_32x32x16_bf16 v[48:63], v[236:239], v[148:151], v[48:63]
	v_add_f32_e32 v243, v215, v243
	v_add_f32_e32 v197, v197, v243
	v_cvt_pk_bf16_f32 v200, v200, v201
	v_cvt_pk_bf16_f32 v201, v202, v203
	v_cvt_pk_bf16_f32 v202, v204, v205
	s_waitcnt lgkmcnt(0)
	v_mfma_f32_32x32x16_bf16 v[16:31], v[248:251], v[148:151], v[16:31]
	v_cvt_pk_bf16_f32 v203, v206, v207
	v_cvt_pk_bf16_f32 v204, v208, v209
	v_cvt_pk_bf16_f32 v205, v210, v211
	v_cvt_pk_bf16_f32 v206, v212, v213
	v_cvt_pk_bf16_f32 v207, v214, v215
	ds_read_b128 v[252:255], v199 offset:4608
	ds_read_b128 v[208:211], v193
	ds_read_b128 v[212:215], v199 offset:4640
	v_mfma_f32_32x32x16_bf16 v[128:143], v[216:219], v[200:203], v[128:143]
	v_mfma_f32_32x32x16_bf16 v[96:111], v[224:227], v[200:203], v[96:111]
	v_mfma_f32_32x32x16_bf16 v[64:79], v[232:235], v[200:203], v[64:79]
	v_mfma_f32_32x32x16_bf16 v[32:47], v[244:247], v[200:203], v[32:47]
	v_mfma_f32_32x32x16_bf16 v[128:143], v[220:223], v[204:207], v[128:143]
	v_mfma_f32_32x32x16_bf16 v[96:111], v[228:231], v[204:207], v[96:111]
	v_mfma_f32_32x32x16_bf16 v[64:79], v[236:239], v[204:207], v[64:79]
	v_mfma_f32_32x32x16_bf16 v[32:47], v[248:251], v[204:207], v[32:47]
	ds_read_b128 v[236:239], v193 offset:32
	ds_read_b128 v[224:227], v199 offset:4672
	ds_read_b128 v[244:247], v193 offset:64
	ds_read_b128 v[228:231], v199 offset:4704
	ds_read_b128 v[248:251], v193 offset:96
	s_waitcnt lgkmcnt(6)
	v_mfma_f32_32x32x16_bf16 v[144:159], v[252:255], v[208:211], v[0:15]
	s_waitcnt lgkmcnt(4)
	v_mfma_f32_32x32x16_bf16 v[144:159], v[212:215], v[236:239], v[144:159]
	s_waitcnt lgkmcnt(2)
	v_mfma_f32_32x32x16_bf16 v[144:159], v[224:227], v[244:247], v[144:159]
	s_waitcnt lgkmcnt(0)
	v_mfma_f32_32x32x16_bf16 v[144:159], v[228:231], v[248:251], v[144:159]
	ds_read_b128 v[216:219], v199 offset:13824
	ds_read_b128 v[232:235], v193 offset:36864
	ds_read_b128 v[220:223], v199 offset:13856
	ds_read_b128 v[236:239], v193 offset:36896
	ds_read_b128 v[224:227], v199 offset:13888
	ds_read_b128 v[244:247], v193 offset:36928
	ds_read_b128 v[228:231], v199 offset:13920
	ds_read_b128 v[248:251], v193 offset:36960
	s_nop 3
	v_exp_f32_e32 v144, v144
	v_exp_f32_e32 v145, v145
	v_exp_f32_e32 v146, v146
	v_exp_f32_e32 v147, v147
	v_exp_f32_e32 v148, v148
	v_exp_f32_e32 v149, v149
	v_exp_f32_e32 v150, v150
	v_exp_f32_e32 v151, v151
	v_exp_f32_e32 v152, v152
	v_exp_f32_e32 v153, v153
	v_exp_f32_e32 v154, v154
	v_exp_f32_e32 v155, v155
	v_exp_f32_e32 v156, v156
	v_exp_f32_e32 v157, v157
	v_exp_f32_e32 v158, v158
	v_exp_f32_e32 v159, v159
	v_add_f32_e32 v243, v144, v145
	v_add_f32_e32 v243, v146, v243
	v_add_f32_e32 v243, v147, v243
	v_add_f32_e32 v243, v148, v243
	v_add_f32_e32 v243, v149, v243
	v_add_f32_e32 v243, v150, v243
	v_add_f32_e32 v243, v151, v243
	s_waitcnt lgkmcnt(6)
	v_mfma_f32_32x32x16_bf16 v[200:215], v[216:219], v[232:235], v[0:15]
	s_waitcnt lgkmcnt(4)
	v_mfma_f32_32x32x16_bf16 v[200:215], v[220:223], v[236:239], v[200:215]
	s_waitcnt lgkmcnt(2)
	v_mfma_f32_32x32x16_bf16 v[200:215], v[224:227], v[244:247], v[200:215]
	s_waitcnt lgkmcnt(0)
	v_mfma_f32_32x32x16_bf16 v[200:215], v[228:231], v[248:251], v[200:215]
	ds_read_b128 v[216:219], v198 offset:64
	ds_read_b128 v[224:227], v198 offset:4672
	ds_read_b128 v[232:235], v198 offset:9280
	ds_read_b128 v[244:247], v198 offset:13888
	ds_read_b128 v[220:223], v198 offset:96
	ds_read_b128 v[228:231], v198 offset:4704
	ds_read_b128 v[236:239], v198 offset:9312
	ds_read_b128 v[248:251], v198 offset:13920
	v_add_f32_e32 v243, v152, v243
	v_add_f32_e32 v243, v153, v243
	v_add_f32_e32 v243, v154, v243
	v_add_f32_e32 v243, v155, v243
	v_add_f32_e32 v243, v156, v243
	v_add_f32_e32 v243, v157, v243
	v_add_f32_e32 v243, v158, v243
	v_add_f32_e32 v243, v159, v243
	v_add_f32_e32 v196, v196, v243
	v_cvt_pk_bf16_f32 v144, v144, v145
	v_cvt_pk_bf16_f32 v145, v146, v147
	v_cvt_pk_bf16_f32 v146, v148, v149
	v_cvt_pk_bf16_f32 v147, v150, v151
	v_cvt_pk_bf16_f32 v148, v152, v153
	v_cvt_pk_bf16_f32 v149, v154, v155
	v_cvt_pk_bf16_f32 v150, v156, v157
	v_cvt_pk_bf16_f32 v151, v158, v159
	s_waitcnt lgkmcnt(7)
	v_mfma_f32_32x32x16_bf16 v[112:127], v[216:219], v[144:147], v[112:127]
	v_exp_f32_e32 v200, v200
	v_exp_f32_e32 v201, v201
	v_exp_f32_e32 v202, v202
	v_exp_f32_e32 v203, v203
	v_exp_f32_e32 v204, v204
	s_waitcnt lgkmcnt(6)
	v_mfma_f32_32x32x16_bf16 v[80:95], v[224:227], v[144:147], v[80:95]
	v_exp_f32_e32 v205, v205
	v_exp_f32_e32 v206, v206
	v_exp_f32_e32 v207, v207
	v_exp_f32_e32 v208, v208
	v_exp_f32_e32 v209, v209
	s_waitcnt lgkmcnt(5)
	v_mfma_f32_32x32x16_bf16 v[48:63], v[232:235], v[144:147], v[48:63]
	v_exp_f32_e32 v210, v210
	v_exp_f32_e32 v211, v211
	v_exp_f32_e32 v212, v212
	v_exp_f32_e32 v213, v213
	v_exp_f32_e32 v214, v214
	s_waitcnt lgkmcnt(4)
	v_mfma_f32_32x32x16_bf16 v[16:31], v[244:247], v[144:147], v[16:31]
	v_exp_f32_e32 v215, v215
	v_add_f32_e32 v243, v200, v201
	v_add_f32_e32 v243, v202, v243
	v_add_f32_e32 v243, v203, v243
	v_add_f32_e32 v243, v204, v243
	s_waitcnt lgkmcnt(3)
	v_mfma_f32_32x32x16_bf16 v[112:127], v[220:223], v[148:151], v[112:127]
	v_add_f32_e32 v243, v205, v243
	v_add_f32_e32 v243, v206, v243
	v_add_f32_e32 v243, v207, v243
	v_add_f32_e32 v243, v208, v243
	v_add_f32_e32 v243, v209, v243
	s_waitcnt lgkmcnt(2)
	v_mfma_f32_32x32x16_bf16 v[80:95], v[228:231], v[148:151], v[80:95]
	v_add_f32_e32 v243, v210, v243
	v_add_f32_e32 v243, v211, v243
	v_add_f32_e32 v243, v212, v243
	v_add_f32_e32 v243, v213, v243
	v_add_f32_e32 v243, v214, v243
	s_waitcnt lgkmcnt(1)
	v_mfma_f32_32x32x16_bf16 v[48:63], v[236:239], v[148:151], v[48:63]
	v_add_f32_e32 v243, v215, v243
	v_add_f32_e32 v197, v197, v243
	v_cvt_pk_bf16_f32 v200, v200, v201
	v_cvt_pk_bf16_f32 v201, v202, v203
	v_cvt_pk_bf16_f32 v202, v204, v205
	s_waitcnt lgkmcnt(0)
	v_mfma_f32_32x32x16_bf16 v[16:31], v[248:251], v[148:151], v[16:31]
	v_cvt_pk_bf16_f32 v203, v206, v207
	v_cvt_pk_bf16_f32 v204, v208, v209
	v_cvt_pk_bf16_f32 v205, v210, v211
	v_cvt_pk_bf16_f32 v206, v212, v213
	v_cvt_pk_bf16_f32 v207, v214, v215
	s_add_i32 s4, s42, 1
	s_cmp_lt_u32 s4, s98
	s_cbranch_scc1 .LBB0_111
	s_nop 1
	v_mfma_f32_32x32x16_bf16 v[128:143], v[216:219], v[200:203], v[128:143]
	v_mfma_f32_32x32x16_bf16 v[96:111], v[224:227], v[200:203], v[96:111]
	v_mfma_f32_32x32x16_bf16 v[64:79], v[232:235], v[200:203], v[64:79]
	v_mfma_f32_32x32x16_bf16 v[32:47], v[244:247], v[200:203], v[32:47]
	v_mfma_f32_32x32x16_bf16 v[128:143], v[220:223], v[204:207], v[128:143]
	v_mfma_f32_32x32x16_bf16 v[96:111], v[228:231], v[204:207], v[96:111]
	v_mfma_f32_32x32x16_bf16 v[64:79], v[236:239], v[204:207], v[64:79]
	v_mfma_f32_32x32x16_bf16 v[32:47], v[248:251], v[204:207], v[32:47]
	s_branch .LBB0_111
